# plus: KV up-projection epilogue row-norm loads issued as one burst; attention unit epilogue gate loads issued up front; MLA steady loop runs one more iteration (all tiles left of the diagonal block)
# speedup vs baseline: 1.0025x; 1.0025x over previous
.LBB0_572:
	s_lshl_b32 s6, s74, 8
	v_mov_b32_e32 v130, v252
	v_mov_b32_e32 v149, v221
	s_add_i32 s6, s6, s41
	s_brev_b32 s16, 60
	v_add_u32_e32 v144, s6, v130
	v_ashrrev_i32_e32 v145, 31, v144
	v_lshl_add_u64 v[130:131], v[144:145], 4, s[88:89]
	global_load_dwordx4 v[206:209], v[130:131], off
	global_load_dwordx4 v[210:213], v[130:131], off offset:256
	global_load_dwordx4 v[214:217], v[130:131], off offset:512
	global_load_dwordx4 v[222:225], v[130:131], off offset:768
	global_load_dwordx4 v[226:229], v[130:131], off offset:2048
	global_load_dwordx4 v[230:233], v[130:131], off offset:2304
	global_load_dwordx4 v[234:237], v[130:131], off offset:2560
	global_load_dwordx4 v[238:241], v[130:131], off offset:2816
	v_add_u32_e32 v146, 16, v144
	v_ashrrev_i32_e32 v147, 31, v146
	s_mov_b32 s6, 0x358637bd
	v_mov_b64_e32 v[150:151], s[6:7]
	v_add_u32_e32 v154, 32, v144
	v_ashrrev_i32_e32 v155, 31, v154
	v_add_u32_e32 v156, 48, v144
	v_ashrrev_i32_e32 v157, 31, v156
	v_add_u32_e32 v160, 0x90, v144
	v_ashrrev_i32_e32 v161, 31, v160
	s_waitcnt vmcnt(7)
	v_mov_b32_e32 v130, v206
	v_mov_b32_e32 v131, v207
	v_mov_b32_e32 v132, v208
	v_mov_b32_e32 v133, v209
	v_mov_b32_e32 v136, v131
	v_mov_b32_e32 v137, v132
	v_mov_b32_e32 v131, v133
	v_pk_add_f32 v[136:137], v[136:137], v[130:131]
	v_lshl_add_u64 v[130:131], v[146:147], 4, s[88:89]
	s_waitcnt vmcnt(6)
	v_mov_b32_e32 v130, v210
	v_mov_b32_e32 v131, v211
	v_mov_b32_e32 v132, v212
	v_mov_b32_e32 v133, v213
	v_mov_b32_e32 v138, v131
	v_mov_b32_e32 v139, v132
	v_mov_b32_e32 v131, v133
	v_pk_add_f32 v[130:131], v[138:139], v[130:131]
	v_mov_b32_e32 v133, v136
	v_mov_b32_e32 v132, v130
	v_mov_b32_e32 v136, v131
	v_pk_add_f32 v[130:131], v[132:133], v[136:137]
	s_nop 0
	v_pk_fma_f32 v[130:131], v[130:131], s[16:17], v[150:151] op_sel_hi:[1,0,0]
	s_nop 0
	v_mul_f32_e32 v132, 0x4b800000, v131
	v_cmp_gt_f32_e64 s[6:7], s29, v131
	v_cmp_gt_f32_e32 vcc, s29, v130
	s_nop 0
	v_cndmask_b32_e64 v131, v131, v132, s[6:7]
	v_rsq_f32_e32 v131, v131
	s_nop 0
	v_mul_f32_e32 v132, 0x45800000, v131
	v_cndmask_b32_e64 v138, v131, v132, s[6:7]
	v_mul_f32_e32 v131, 0x4b800000, v130
	v_cndmask_b32_e32 v130, v130, v131, vcc
	v_rsq_f32_e32 v130, v130
	v_pk_mul_f32 v[124:125], v[124:125], v[138:139] op_sel_hi:[1,0]
	v_pk_mul_f32 v[122:123], v[122:123], v[138:139] op_sel_hi:[1,0]
	v_pk_mul_f32 v[128:129], v[128:129], v[138:139] op_sel_hi:[1,0]
	v_mul_f32_e32 v131, 0x45800000, v130
	v_cndmask_b32_e32 v136, v130, v131, vcc
	v_lshl_add_u64 v[130:131], v[154:155], 4, s[88:89]
	v_cvt_pk_bf16_f32 v122, v122, v123
	v_cvt_pk_bf16_f32 v123, v124, v125
	v_pk_mul_f32 v[108:109], v[108:109], v[136:137] op_sel_hi:[1,0]
	v_pk_mul_f32 v[106:107], v[106:107], v[136:137] op_sel_hi:[1,0]
	v_pk_mul_f32 v[126:127], v[126:127], v[138:139] op_sel_hi:[1,0]
	v_cvt_pk_bf16_f32 v106, v106, v107
	v_cvt_pk_bf16_f32 v107, v108, v109
	v_pk_mul_f32 v[112:113], v[112:113], v[136:137] op_sel_hi:[1,0]
	v_pk_mul_f32 v[110:111], v[110:111], v[136:137] op_sel_hi:[1,0]
	v_pk_mul_f32 v[56:57], v[56:57], v[138:139] op_sel_hi:[1,0]
	v_pk_mul_f32 v[54:55], v[54:55], v[138:139] op_sel_hi:[1,0]
	v_cvt_pk_bf16_f32 v126, v126, v127
	v_cvt_pk_bf16_f32 v127, v128, v129
	v_cvt_pk_bf16_f32 v110, v110, v111
	v_cvt_pk_bf16_f32 v111, v112, v113
	v_cvt_pk_bf16_f32 v54, v54, v55
	v_cvt_pk_bf16_f32 v55, v56, v57
	v_pk_mul_f32 v[40:41], v[40:41], v[136:137] op_sel_hi:[1,0]
	v_pk_mul_f32 v[38:39], v[38:39], v[136:137] op_sel_hi:[1,0]
	v_pk_mul_f32 v[64:65], v[64:65], v[138:139] op_sel_hi:[1,0]
	v_cvt_pk_bf16_f32 v38, v38, v39
	v_cvt_pk_bf16_f32 v39, v40, v41
	v_pk_mul_f32 v[62:63], v[62:63], v[138:139] op_sel_hi:[1,0]
	v_pk_mul_f32 v[48:49], v[48:49], v[136:137] op_sel_hi:[1,0]
	v_pk_mul_f32 v[46:47], v[46:47], v[136:137] op_sel_hi:[1,0]
	v_cvt_pk_bf16_f32 v62, v62, v63
	v_cvt_pk_bf16_f32 v63, v64, v65
	v_cvt_pk_bf16_f32 v46, v46, v47
	v_cvt_pk_bf16_f32 v47, v48, v49
	s_waitcnt vmcnt(5)
	v_mov_b32_e32 v130, v214
	v_mov_b32_e32 v131, v215
	v_mov_b32_e32 v132, v216
	v_mov_b32_e32 v133, v217
	v_mov_b32_e32 v152, v131
	v_mov_b32_e32 v153, v132
	v_mov_b32_e32 v131, v133
	v_pk_add_f32 v[152:153], v[152:153], v[130:131]
	v_lshl_add_u64 v[130:131], v[156:157], 4, s[88:89]
	s_waitcnt vmcnt(4)
	v_mov_b32_e32 v130, v222
	v_mov_b32_e32 v131, v223
	v_mov_b32_e32 v132, v224
	v_mov_b32_e32 v133, v225
	v_mov_b32_e32 v158, v131
	v_mov_b32_e32 v159, v132
	v_mov_b32_e32 v131, v133
	v_pk_add_f32 v[130:131], v[158:159], v[130:131]
	v_mov_b32_e32 v133, v152
	v_mov_b32_e32 v132, v130
	v_mov_b32_e32 v152, v131
	v_pk_add_f32 v[130:131], v[132:133], v[152:153]
	v_add_u32_e32 v158, 0x80, v144
	v_pk_fma_f32 v[130:131], v[130:131], s[16:17], v[150:151] op_sel_hi:[1,0,0]
	v_ashrrev_i32_e32 v159, 31, v158
	v_mul_f32_e32 v132, 0x4b800000, v131
	v_cmp_gt_f32_e64 s[6:7], s29, v131
	v_cmp_gt_f32_e32 vcc, s29, v130
	s_nop 0
	v_cndmask_b32_e64 v131, v131, v132, s[6:7]
	v_rsq_f32_e32 v131, v131
	s_nop 0
	v_mul_f32_e32 v132, 0x45800000, v131
	v_cndmask_b32_e64 v142, v131, v132, s[6:7]
	v_mul_f32_e32 v131, 0x4b800000, v130
	v_cndmask_b32_e32 v130, v130, v131, vcc
	v_rsq_f32_e32 v130, v130
	v_pk_mul_f32 v[92:93], v[92:93], v[142:143] op_sel_hi:[1,0]
	v_pk_mul_f32 v[90:91], v[90:91], v[142:143] op_sel_hi:[1,0]
	v_pk_mul_f32 v[96:97], v[96:97], v[142:143] op_sel_hi:[1,0]
	v_mul_f32_e32 v131, 0x45800000, v130
	v_cndmask_b32_e32 v140, v130, v131, vcc
	v_lshl_add_u64 v[130:131], v[158:159], 4, s[88:89]
	v_cvt_pk_bf16_f32 v90, v90, v91
	v_cvt_pk_bf16_f32 v91, v92, v93
	v_pk_mul_f32 v[80:81], v[80:81], v[140:141] op_sel_hi:[1,0]
	v_pk_mul_f32 v[78:79], v[78:79], v[140:141] op_sel_hi:[1,0]
	v_pk_mul_f32 v[76:77], v[76:77], v[140:141] op_sel_hi:[1,0]
	v_pk_mul_f32 v[74:75], v[74:75], v[140:141] op_sel_hi:[1,0]
	v_cvt_pk_bf16_f32 v78, v78, v79
	v_cvt_pk_bf16_f32 v79, v80, v81
	v_cvt_pk_bf16_f32 v74, v74, v75
	v_cvt_pk_bf16_f32 v75, v76, v77
	v_pk_mul_f32 v[94:95], v[94:95], v[142:143] op_sel_hi:[1,0]
	v_pk_mul_f32 v[24:25], v[24:25], v[142:143] op_sel_hi:[1,0]
	v_cvt_pk_bf16_f32 v94, v94, v95
	v_cvt_pk_bf16_f32 v95, v96, v97
	v_pk_mul_f32 v[22:23], v[22:23], v[142:143] op_sel_hi:[1,0]
	v_pk_mul_f32 v[16:17], v[16:17], v[140:141] op_sel_hi:[1,0]
	v_cvt_pk_bf16_f32 v22, v22, v23
	v_cvt_pk_bf16_f32 v23, v24, v25
	v_pk_mul_f32 v[14:15], v[14:15], v[140:141] op_sel_hi:[1,0]
	v_pk_mul_f32 v[6:7], v[6:7], v[140:141] op_sel_hi:[1,0]
	v_cvt_pk_bf16_f32 v14, v14, v15
	v_cvt_pk_bf16_f32 v15, v16, v17
	v_pk_mul_f32 v[4:5], v[4:5], v[140:141] op_sel_hi:[1,0]
	v_pk_mul_f32 v[32:33], v[32:33], v[142:143] op_sel_hi:[1,0]
	v_cvt_pk_bf16_f32 v4, v4, v5
	v_cvt_pk_bf16_f32 v5, v6, v7
	v_pk_mul_f32 v[30:31], v[30:31], v[142:143] op_sel_hi:[1,0]
	s_waitcnt vmcnt(3)
	v_mov_b32_e32 v130, v226
	v_mov_b32_e32 v131, v227
	v_mov_b32_e32 v132, v228
	v_mov_b32_e32 v133, v229
	v_mov_b32_e32 v152, v131
	v_mov_b32_e32 v153, v132
	v_mov_b32_e32 v131, v133
	v_pk_add_f32 v[152:153], v[152:153], v[130:131]
	v_lshl_add_u64 v[130:131], v[160:161], 4, s[88:89]
	v_cvt_pk_bf16_f32 v30, v30, v31
	v_cvt_pk_bf16_f32 v31, v32, v33
	s_waitcnt vmcnt(2)
	v_mov_b32_e32 v130, v230
	v_mov_b32_e32 v131, v231
	v_mov_b32_e32 v132, v232
	v_mov_b32_e32 v133, v233
	v_mov_b32_e32 v162, v131
	v_mov_b32_e32 v163, v132
	v_mov_b32_e32 v131, v133
	v_pk_add_f32 v[130:131], v[162:163], v[130:131]
	v_mov_b32_e32 v133, v152
	v_mov_b32_e32 v132, v130
	v_mov_b32_e32 v152, v131
	v_pk_add_f32 v[130:131], v[132:133], v[152:153]
	v_add_u32_e32 v162, 0xa0, v144
	v_pk_fma_f32 v[130:131], v[130:131], s[16:17], v[150:151] op_sel_hi:[1,0,0]
	v_ashrrev_i32_e32 v163, 31, v162
	v_mul_f32_e32 v132, 0x4b800000, v131
	v_cmp_gt_f32_e64 s[6:7], s29, v131
	v_cmp_gt_f32_e32 vcc, s29, v130
	s_nop 0
	v_cndmask_b32_e64 v131, v131, v132, s[6:7]
	v_rsq_f32_e32 v131, v131
	s_nop 0
	v_mul_f32_e32 v132, 0x45800000, v131
	v_cndmask_b32_e64 v152, v131, v132, s[6:7]
	v_mul_f32_e32 v131, 0x4b800000, v130
	v_cndmask_b32_e32 v130, v130, v131, vcc
	v_rsq_f32_e32 v130, v130
	v_pk_mul_f32 v[80:81], v[118:119], v[152:153] op_sel_hi:[1,0]
	v_pk_mul_f32 v[6:7], v[60:61], v[152:153] op_sel_hi:[1,0]
	v_cvt_pk_bf16_f32 v80, v80, v81
	v_mul_f32_e32 v131, 0x45800000, v130
	v_cndmask_b32_e32 v148, v130, v131, vcc
	v_lshl_add_u64 v[130:131], v[162:163], 4, s[88:89]
	s_waitcnt vmcnt(1)
	v_mov_b32_e32 v130, v234
	v_mov_b32_e32 v131, v235
	v_mov_b32_e32 v132, v236
	v_mov_b32_e32 v133, v237
	v_mov_b32_e32 v164, v131
	v_mov_b32_e32 v165, v132
	v_mov_b32_e32 v131, v133
	v_pk_add_f32 v[178:179], v[164:165], v[130:131]
	v_add_u32_e32 v164, 0xb0, v144
	v_ashrrev_i32_e32 v165, 31, v164
	v_lshl_add_u64 v[130:131], v[164:165], 4, s[88:89]
	v_lshlrev_b64 v[144:145], 10, v[144:145]
	s_waitcnt vmcnt(0)
	v_mov_b32_e32 v130, v238
	v_mov_b32_e32 v131, v239
	v_mov_b32_e32 v132, v240
	v_mov_b32_e32 v133, v241
	v_mov_b32_e32 v168, v131
	v_mov_b32_e32 v169, v132
	v_mov_b32_e32 v131, v133
	v_pk_add_f32 v[130:131], v[168:169], v[130:131]
	v_mov_b32_e32 v133, v178
	v_mov_b32_e32 v132, v130
	v_mov_b32_e32 v178, v131
	v_pk_add_f32 v[130:131], v[132:133], v[178:179]
	s_nop 0
	v_pk_fma_f32 v[132:133], v[130:131], s[16:17], v[150:151] op_sel_hi:[1,0,0]
	s_nop 0
	v_mul_f32_e32 v130, 0x4b800000, v133
	v_cmp_gt_f32_e64 s[6:7], s29, v133
	v_cmp_gt_f32_e32 vcc, s29, v132
	s_nop 0
	v_cndmask_b32_e64 v130, v133, v130, s[6:7]
	v_rsq_f32_e32 v130, v130
	s_nop 0
	v_mul_f32_e32 v131, 0x45800000, v130
	v_cndmask_b32_e64 v130, v130, v131, s[6:7]
	s_lshl_b32 s6, s67, 7
	s_or_b32 s6, s6, s66
	v_lshl_add_u32 v150, v149, 2, s6
	v_ashrrev_i32_e32 v151, 31, v150
	v_lshl_add_u64 v[168:169], v[150:151], 1, s[12:13]
	v_lshl_add_u64 v[170:171], v[168:169], 0, v[144:145]
	global_store_dwordx2 v[170:171], v[122:123], off offset:32
	v_lshlrev_b64 v[122:123], 10, v[146:147]
	v_lshl_add_u64 v[124:125], v[168:169], 0, v[122:123]
	global_store_dwordx2 v[124:125], v[106:107], off offset:32
	v_lshlrev_b64 v[106:107], 10, v[154:155]
	v_lshl_add_u64 v[108:109], v[168:169], 0, v[106:107]
	global_store_dwordx2 v[108:109], v[90:91], off offset:32
	v_lshlrev_b64 v[90:91], 10, v[156:157]
	v_lshl_add_u64 v[92:93], v[168:169], 0, v[90:91]
	global_store_dwordx2 v[92:93], v[78:79], off
	global_store_dwordx2 v[92:93], v[74:75], off offset:32
	v_lshlrev_b64 v[74:75], 10, v[158:159]
	v_pk_mul_f32 v[78:79], v[120:121], v[152:153] op_sel_hi:[1,0]
	v_lshl_add_u64 v[76:77], v[168:169], 0, v[74:75]
	v_cvt_pk_bf16_f32 v81, v78, v79
	v_mul_f32_e32 v131, 0x4b800000, v132
	global_store_dwordx2 v[76:77], v[80:81], off
	v_pk_mul_f32 v[78:79], v[116:117], v[152:153] op_sel_hi:[1,0]
	v_pk_mul_f32 v[80:81], v[114:115], v[152:153] op_sel_hi:[1,0]
	v_cndmask_b32_e32 v131, v132, v131, vcc
	v_cvt_pk_bf16_f32 v80, v80, v81
	v_cvt_pk_bf16_f32 v81, v78, v79
	v_rsq_f32_e32 v131, v131
	global_store_dwordx2 v[76:77], v[80:81], off offset:32
	v_lshlrev_b64 v[76:77], 10, v[160:161]
	v_pk_mul_f32 v[80:81], v[104:105], v[148:149] op_sel_hi:[1,0]
	v_pk_mul_f32 v[92:93], v[102:103], v[148:149] op_sel_hi:[1,0]
	v_lshl_add_u64 v[78:79], v[168:169], 0, v[76:77]
	v_cvt_pk_bf16_f32 v92, v92, v93
	v_cvt_pk_bf16_f32 v93, v80, v81
	global_store_dwordx2 v[78:79], v[92:93], off
	v_pk_mul_f32 v[80:81], v[100:101], v[148:149] op_sel_hi:[1,0]
	v_pk_mul_f32 v[92:93], v[98:99], v[148:149] op_sel_hi:[1,0]
	v_mul_f32_e32 v132, 0x45800000, v131
	v_cvt_pk_bf16_f32 v92, v92, v93
	v_cvt_pk_bf16_f32 v93, v80, v81
	global_store_dwordx2 v[78:79], v[92:93], off offset:32
	v_lshlrev_b64 v[78:79], 10, v[162:163]
	v_pk_mul_f32 v[88:89], v[88:89], v[130:131] op_sel_hi:[1,0]
	v_pk_mul_f32 v[86:87], v[86:87], v[130:131] op_sel_hi:[1,0]
	v_pk_mul_f32 v[84:85], v[84:85], v[130:131] op_sel_hi:[1,0]
	v_pk_mul_f32 v[82:83], v[82:83], v[130:131] op_sel_hi:[1,0]
	v_cndmask_b32_e32 v132, v131, v132, vcc
	v_lshl_add_u64 v[80:81], v[168:169], 0, v[78:79]
	v_cvt_pk_bf16_f32 v86, v86, v87
	v_cvt_pk_bf16_f32 v87, v88, v89
	v_cvt_pk_bf16_f32 v82, v82, v83
	v_cvt_pk_bf16_f32 v83, v84, v85
	global_store_dwordx2 v[80:81], v[86:87], off
	global_store_dwordx2 v[80:81], v[82:83], off offset:32
	v_lshlrev_b64 v[80:81], 10, v[164:165]
	v_pk_mul_f32 v[68:69], v[68:69], v[132:133] op_sel_hi:[1,0]
	v_pk_mul_f32 v[66:67], v[66:67], v[132:133] op_sel_hi:[1,0]
	v_lshl_add_u64 v[82:83], v[168:169], 0, v[80:81]
	v_cvt_pk_bf16_f32 v66, v66, v67
	v_cvt_pk_bf16_f32 v67, v68, v69
	global_store_dwordx2 v[82:83], v[66:67], off offset:32
	v_add_u32_e32 v66, 64, v150
	v_ashrrev_i32_e32 v67, 31, v66
	v_pk_mul_f32 v[72:73], v[72:73], v[132:133] op_sel_hi:[1,0]
	v_pk_mul_f32 v[70:71], v[70:71], v[132:133] op_sel_hi:[1,0]
	v_lshl_add_u64 v[66:67], v[66:67], 1, s[12:13]
	v_cvt_pk_bf16_f32 v70, v70, v71
	v_cvt_pk_bf16_f32 v71, v72, v73
	v_lshl_add_u64 v[68:69], v[66:67], 0, v[144:145]
	global_store_dwordx2 v[170:171], v[126:127], off
	global_store_dwordx2 v[124:125], v[110:111], off
	global_store_dwordx2 v[108:109], v[94:95], off
	global_store_dwordx2 v[82:83], v[70:71], off
	global_store_dwordx2 v[68:69], v[54:55], off offset:32
	v_lshl_add_u64 v[54:55], v[66:67], 0, v[122:123]
	global_store_dwordx2 v[54:55], v[38:39], off offset:32
	v_lshl_add_u64 v[38:39], v[66:67], 0, v[106:107]
	global_store_dwordx2 v[38:39], v[22:23], off offset:32
	v_lshl_add_u64 v[22:23], v[66:67], 0, v[90:91]
	global_store_dwordx2 v[22:23], v[14:15], off
	v_pk_mul_f32 v[14:15], v[58:59], v[152:153] op_sel_hi:[1,0]
	global_store_dwordx2 v[22:23], v[4:5], off offset:32
	v_lshl_add_u64 v[4:5], v[66:67], 0, v[74:75]
	v_cvt_pk_bf16_f32 v14, v14, v15
	v_cvt_pk_bf16_f32 v15, v6, v7
	global_store_dwordx2 v[4:5], v[14:15], off
	v_pk_mul_f32 v[6:7], v[52:53], v[152:153] op_sel_hi:[1,0]
	v_pk_mul_f32 v[14:15], v[50:51], v[152:153] op_sel_hi:[1,0]
	v_pk_mul_f32 v[8:9], v[8:9], v[132:133] op_sel_hi:[1,0]
	v_cvt_pk_bf16_f32 v14, v14, v15
	v_cvt_pk_bf16_f32 v15, v6, v7
	global_store_dwordx2 v[4:5], v[14:15], off offset:32
	v_pk_mul_f32 v[6:7], v[44:45], v[148:149] op_sel_hi:[1,0]
	v_pk_mul_f32 v[14:15], v[42:43], v[148:149] op_sel_hi:[1,0]
	v_lshl_add_u64 v[4:5], v[66:67], 0, v[76:77]
	v_cvt_pk_bf16_f32 v14, v14, v15
	v_cvt_pk_bf16_f32 v15, v6, v7
	global_store_dwordx2 v[4:5], v[14:15], off
	v_pk_mul_f32 v[6:7], v[36:37], v[148:149] op_sel_hi:[1,0]
	v_pk_mul_f32 v[14:15], v[34:35], v[148:149] op_sel_hi:[1,0]
	v_pk_mul_f32 v[2:3], v[2:3], v[132:133] op_sel_hi:[1,0]
	v_cvt_pk_bf16_f32 v14, v14, v15
	v_cvt_pk_bf16_f32 v15, v6, v7
	global_store_dwordx2 v[4:5], v[14:15], off offset:32
	v_pk_mul_f32 v[6:7], v[28:29], v[130:131] op_sel_hi:[1,0]
	v_pk_mul_f32 v[14:15], v[26:27], v[130:131] op_sel_hi:[1,0]
	v_lshl_add_u64 v[4:5], v[66:67], 0, v[78:79]
	v_cvt_pk_bf16_f32 v14, v14, v15
	v_cvt_pk_bf16_f32 v15, v6, v7
	global_store_dwordx2 v[4:5], v[14:15], off
	v_pk_mul_f32 v[6:7], v[20:21], v[130:131] op_sel_hi:[1,0]
	v_pk_mul_f32 v[14:15], v[18:19], v[130:131] op_sel_hi:[1,0]
	v_pk_mul_f32 v[0:1], v[0:1], v[132:133] op_sel_hi:[1,0]
	v_cvt_pk_bf16_f32 v14, v14, v15
	v_cvt_pk_bf16_f32 v15, v6, v7
	v_pk_mul_f32 v[6:7], v[10:11], v[132:133] op_sel_hi:[1,0]
	global_store_dwordx2 v[4:5], v[14:15], off offset:32
	v_lshl_add_u64 v[4:5], v[66:67], 0, v[80:81]
	v_cvt_pk_bf16_f32 v8, v8, v9
	v_cvt_pk_bf16_f32 v9, v6, v7
	v_cvt_pk_bf16_f32 v0, v0, v1
	v_cvt_pk_bf16_f32 v1, v2, v3
	s_mov_b64 s[6:7], -1
	s_andn2_b64 vcc, exec, s[4:5]
	global_store_dwordx2 v[68:69], v[62:63], off
	global_store_dwordx2 v[54:55], v[46:47], off
	global_store_dwordx2 v[38:39], v[30:31], off
	global_store_dwordx2 v[4:5], v[8:9], off
	global_store_dwordx2 v[4:5], v[0:1], off offset:32
	s_cbranch_vccnz .LBB0_563
	s_andn2_b64 vcc, exec, s[8:9]
	s_cbranch_vccnz .LBB0_562
	s_barrier
	s_branch .LBB0_562

.LBB0_630:
	v_readlane_b32 s4, v253, 38
	v_lshlrev_b64 v[0:1], 1, v[134:135]
	v_readlane_b32 s5, v253, 39
	v_pk_mul_f32 v[10:11], v[16:17], v[2:3] op_sel_hi:[1,0]
	v_pk_mul_f32 v[14:15], v[14:15], v[2:3] op_sel_hi:[1,0]
	v_lshl_add_u64 v[4:5], s[4:5], 0, v[0:1]
	global_load_dwordx2 v[190:191], v[4:5], off
	global_load_dwordx2 v[192:193], v[4:5], off offset:64
	global_load_dwordx2 v[194:195], v[4:5], off offset:16
	global_load_dwordx2 v[196:197], v[4:5], off offset:80
	global_load_dwordx2 v[198:199], v[4:5], off offset:32
	global_load_dwordx2 v[200:201], v[4:5], off offset:96
	global_load_dwordx2 v[202:203], v[4:5], off offset:48
	global_load_dwordx2 v[204:205], v[4:5], off offset:112
	v_pk_mul_f32 v[16:17], v[32:33], v[2:3] op_sel_hi:[1,0]
	v_pk_mul_f32 v[30:31], v[30:31], v[2:3] op_sel_hi:[1,0]
	v_lshl_add_u64 v[0:1], s[70:71], 0, v[0:1]
	s_mov_b64 s[4:5], 0
	s_waitcnt vmcnt(7)
	v_mov_b32_e32 v6, v190
	v_mov_b32_e32 v7, v191
	v_lshlrev_b32_e32 v32, 16, v6
	v_and_b32_e32 v33, 0xffff0000, v6
	v_lshlrev_b32_e32 v6, 16, v7
	v_and_b32_e32 v7, 0xffff0000, v7
	v_pk_mul_f32 v[6:7], v[10:11], v[6:7]
	v_pk_mul_f32 v[10:11], v[14:15], v[32:33]
	s_waitcnt vmcnt(6)
	v_mov_b32_e32 v8, v192
	v_mov_b32_e32 v9, v193
	v_lshlrev_b32_e32 v14, 16, v8
	v_and_b32_e32 v15, 0xffff0000, v8
	v_lshlrev_b32_e32 v8, 16, v9
	v_and_b32_e32 v9, 0xffff0000, v9
	v_pk_mul_f32 v[8:9], v[16:17], v[8:9]
	v_pk_mul_f32 v[14:15], v[30:31], v[14:15]
	v_cvt_pk_bf16_f32 v10, v10, v11
	v_cvt_pk_bf16_f32 v11, v6, v7
	v_cvt_pk_bf16_f32 v6, v14, v15
	v_cvt_pk_bf16_f32 v7, v8, v9
	global_store_dwordx2 v[0:1], v[10:11], off
	global_store_dwordx2 v[0:1], v[6:7], off offset:64
	v_pk_mul_f32 v[14:15], v[20:21], v[2:3] op_sel_hi:[1,0]
	v_pk_mul_f32 v[10:11], v[18:19], v[2:3] op_sel_hi:[1,0]
	v_pk_mul_f32 v[16:17], v[34:35], v[2:3] op_sel_hi:[1,0]
	v_pk_mul_f32 v[18:19], v[36:37], v[2:3] op_sel_hi:[1,0]
	s_waitcnt vmcnt(7)
	v_mov_b32_e32 v6, v194
	v_mov_b32_e32 v7, v195
	v_lshlrev_b32_e32 v20, 16, v6
	v_and_b32_e32 v21, 0xffff0000, v6
	v_lshlrev_b32_e32 v6, 16, v7
	v_and_b32_e32 v7, 0xffff0000, v7
	v_pk_mul_f32 v[6:7], v[14:15], v[6:7]
	s_waitcnt vmcnt(6)
	v_mov_b32_e32 v8, v196
	v_mov_b32_e32 v9, v197
	v_lshlrev_b32_e32 v14, 16, v8
	v_and_b32_e32 v15, 0xffff0000, v8
	v_lshlrev_b32_e32 v8, 16, v9
	v_and_b32_e32 v9, 0xffff0000, v9
	v_pk_mul_f32 v[10:11], v[10:11], v[20:21]
	v_pk_mul_f32 v[8:9], v[18:19], v[8:9]
	v_pk_mul_f32 v[14:15], v[16:17], v[14:15]
	v_cvt_pk_bf16_f32 v10, v10, v11
	v_cvt_pk_bf16_f32 v11, v6, v7
	v_cvt_pk_bf16_f32 v6, v14, v15
	v_cvt_pk_bf16_f32 v7, v8, v9
	global_store_dwordx2 v[0:1], v[10:11], off offset:16
	global_store_dwordx2 v[0:1], v[6:7], off offset:80
	v_pk_mul_f32 v[14:15], v[24:25], v[2:3] op_sel_hi:[1,0]
	v_pk_mul_f32 v[10:11], v[22:23], v[2:3] op_sel_hi:[1,0]
	v_pk_mul_f32 v[16:17], v[38:39], v[2:3] op_sel_hi:[1,0]
	v_pk_mul_f32 v[18:19], v[40:41], v[2:3] op_sel_hi:[1,0]
	s_waitcnt vmcnt(7)
	v_mov_b32_e32 v6, v198
	v_mov_b32_e32 v7, v199
	v_lshlrev_b32_e32 v20, 16, v6
	v_and_b32_e32 v21, 0xffff0000, v6
	v_lshlrev_b32_e32 v6, 16, v7
	v_and_b32_e32 v7, 0xffff0000, v7
	v_pk_mul_f32 v[6:7], v[14:15], v[6:7]
	s_waitcnt vmcnt(6)
	v_mov_b32_e32 v8, v200
	v_mov_b32_e32 v9, v201
	v_lshlrev_b32_e32 v14, 16, v8
	v_and_b32_e32 v15, 0xffff0000, v8
	v_lshlrev_b32_e32 v8, 16, v9
	v_and_b32_e32 v9, 0xffff0000, v9
	v_pk_mul_f32 v[10:11], v[10:11], v[20:21]
	v_pk_mul_f32 v[8:9], v[18:19], v[8:9]
	v_pk_mul_f32 v[14:15], v[16:17], v[14:15]
	v_cvt_pk_bf16_f32 v10, v10, v11
	v_cvt_pk_bf16_f32 v11, v6, v7
	v_cvt_pk_bf16_f32 v6, v14, v15
	v_cvt_pk_bf16_f32 v7, v8, v9
	global_store_dwordx2 v[0:1], v[10:11], off offset:32
	global_store_dwordx2 v[0:1], v[6:7], off offset:96
	v_pk_mul_f32 v[10:11], v[28:29], v[2:3] op_sel_hi:[1,0]
	v_pk_mul_f32 v[8:9], v[26:27], v[2:3] op_sel_hi:[1,0]
	v_pk_mul_f32 v[14:15], v[42:43], v[2:3] op_sel_hi:[1,0]
	v_pk_mul_f32 v[2:3], v[44:45], v[2:3] op_sel_hi:[1,0]
	s_waitcnt vmcnt(7)
	v_mov_b32_e32 v6, v202
	v_mov_b32_e32 v7, v203
	v_lshlrev_b32_e32 v16, 16, v6
	v_and_b32_e32 v17, 0xffff0000, v6
	v_lshlrev_b32_e32 v6, 16, v7
	v_and_b32_e32 v7, 0xffff0000, v7
	v_pk_mul_f32 v[6:7], v[10:11], v[6:7]
	s_waitcnt vmcnt(6)
	v_mov_b32_e32 v4, v204
	v_mov_b32_e32 v5, v205
	v_lshlrev_b32_e32 v10, 16, v4
	v_and_b32_e32 v11, 0xffff0000, v4
	v_lshlrev_b32_e32 v4, 16, v5
	v_and_b32_e32 v5, 0xffff0000, v5
	v_pk_mul_f32 v[8:9], v[8:9], v[16:17]
	v_pk_mul_f32 v[2:3], v[2:3], v[4:5]
	v_pk_mul_f32 v[4:5], v[14:15], v[10:11]
	v_cvt_pk_bf16_f32 v8, v8, v9
	v_cvt_pk_bf16_f32 v9, v6, v7
	v_cvt_pk_bf16_f32 v4, v4, v5
	v_cvt_pk_bf16_f32 v5, v2, v3
	global_store_dwordx2 v[0:1], v[8:9], off offset:48
	global_store_dwordx2 v[0:1], v[4:5], off offset:112

.Lmla_resc_ret0:
	s_waitcnt lgkmcnt(7)
	v_mfma_f32_32x32x16_bf16 v[78:93], v[134:137], v[0:3], v[190:205]
	ds_read_b64_tr_b16 v[134:135], v161 offset:26624
	ds_read_b64_tr_b16 v[136:137], v161 offset:27136
	v_exp_f32_e32 v46, v46
	v_exp_f32_e32 v47, v47
	v_exp_f32_e32 v48, v48
	v_exp_f32_e32 v49, v49
	s_waitcnt lgkmcnt(8)
	v_mfma_f32_32x32x16_bf16 v[94:109], v[138:141], v[0:3], v[190:205]
	ds_read_b64_tr_b16 v[138:139], v161 offset:30720
	ds_read_b64_tr_b16 v[140:141], v161 offset:31232
	v_exp_f32_e32 v50, v50
	v_exp_f32_e32 v51, v51
	v_exp_f32_e32 v52, v52
	v_exp_f32_e32 v53, v53
	s_waitcnt lgkmcnt(9)
	v_mfma_f32_32x32x16_bf16 v[78:93], v[142:145], v[4:7], v[78:93]
	ds_read_b64_tr_b16 v[142:143], v161 offset:27648
	ds_read_b64_tr_b16 v[144:145], v161 offset:28160
	v_cvt_pk_bf16_f32 v152, v46, v47
	v_cvt_pk_bf16_f32 v153, v48, v49
	v_cvt_pk_bf16_f32 v154, v50, v51
	v_cvt_pk_bf16_f32 v155, v52, v53
	s_waitcnt lgkmcnt(10)
	v_mfma_f32_32x32x16_bf16 v[94:109], v[168:171], v[4:7], v[94:109]
	ds_read_b64_tr_b16 v[168:169], v161 offset:31744
	ds_read_b64_tr_b16 v[170:171], v161 offset:32256
	v_exp_f32_e32 v54, v54
	v_exp_f32_e32 v55, v55
	v_exp_f32_e32 v56, v56
	v_exp_f32_e32 v57, v57
	s_waitcnt lgkmcnt(11)
	v_mfma_f32_32x32x16_bf16 v[78:93], v[172:175], v[8:11], v[78:93]
	ds_read_b64_tr_b16 v[172:173], v161 offset:28672
	ds_read_b64_tr_b16 v[174:175], v161 offset:29184
	v_exp_f32_e32 v58, v58
	v_exp_f32_e32 v59, v59
	v_exp_f32_e32 v60, v60
	s_waitcnt lgkmcnt(12)
	v_mfma_f32_32x32x16_bf16 v[94:109], v[178:181], v[8:11], v[94:109]
	ds_read_b64_tr_b16 v[178:179], v161 offset:32768
	ds_read_b64_tr_b16 v[180:181], v161 offset:33280
	v_exp_f32_e32 v61, v61
	v_add_f32_e32 v238, v46, v47
	v_add_f32_e32 v239, v48, v49
	v_add_f32_e32 v242, v50, v51
	v_add_f32_e32 v243, v52, v53
	v_exp_f32_e32 v62, v62
	s_waitcnt lgkmcnt(13)
	v_mfma_f32_32x32x16_bf16 v[78:93], v[182:185], v[110:113], v[78:93]
	ds_read_b64_tr_b16 v[182:183], v161 offset:29696
	ds_read_b64_tr_b16 v[184:185], v161 offset:30208
	v_exp_f32_e32 v63, v63
	v_exp_f32_e32 v64, v64
	v_exp_f32_e32 v65, v65
	v_exp_f32_e32 v66, v66
	s_waitcnt lgkmcnt(14)
	v_mfma_f32_32x32x16_bf16 v[94:109], v[186:189], v[110:113], v[94:109]
	s_waitcnt lgkmcnt(13)
	ds_read_b64_tr_b16 v[186:187], v161 offset:33792
	ds_read_b64_tr_b16 v[188:189], v161 offset:34304
	v_exp_f32_e32 v67, v67
	v_exp_f32_e32 v68, v68
	v_exp_f32_e32 v69, v69
	v_mfma_f32_32x32x16_bf16 v[78:93], v[206:209], v[114:117], v[78:93]
	v_add_f32_e32 v238, v238, v54
	v_add_f32_e32 v239, v239, v55
	v_add_f32_e32 v242, v242, v56
	v_add_f32_e32 v243, v243, v57
	v_add_f32_e32 v238, v238, v58
	v_add_f32_e32 v239, v239, v59
	v_add_f32_e32 v242, v242, v60
	s_waitcnt lgkmcnt(8)
	s_waitcnt vmcnt(0)
	ds_write_b128 v158, v[126:129]
	s_and_saveexec_b64 s[4:5], s[6:7]
	s_cbranch_execz .Lmla_nokw0
	ds_write_b128 v163, v[122:125] offset:128
.Lmla_nokw0:
	s_or_b64 exec, exec, s[4:5]
	ds_write_b128 v159, v[130:133] offset:34816
	v_mfma_f32_32x32x16_bf16 v[94:109], v[210:213], v[114:117], v[94:109]
	v_add_f32_e32 v243, v243, v61
	v_exp_f32_e32 v70, v70
	v_exp_f32_e32 v71, v71
	v_exp_f32_e32 v72, v72
	v_mfma_f32_32x32x16_bf16 v[78:93], v[214:217], v[118:121], v[78:93]
	v_exp_f32_e32 v73, v73
	v_exp_f32_e32 v74, v74
	v_exp_f32_e32 v75, v75
	v_exp_f32_e32 v76, v76
	v_mfma_f32_32x32x16_bf16 v[94:109], v[248:251], v[118:121], v[94:109]
	v_exp_f32_e32 v77, v77
	v_add_f32_e32 v238, v238, v62
	v_add_f32_e32 v239, v239, v63
	v_add_f32_e32 v242, v242, v64
	v_add_f32_e32 v243, v243, v65
	s_waitcnt lgkmcnt(0)
	s_barrier
	ds_read_b128 v[206:209], v162 offset:128
	ds_read_b128 v[210:213], v162 offset:6784
	ds_read_b128 v[214:217], v162 offset:160
	ds_read_b128 v[248:251], v162 offset:6816
	v_mfma_f32_32x32x16_bf16 v[14:29], v[134:137], v[152:155], v[14:29]
	ds_read_b128 v[134:137], v162
	v_cvt_pk_bf16_f32 v222, v54, v55
	v_cvt_pk_bf16_f32 v223, v56, v57
	v_cvt_pk_bf16_f32 v224, v58, v59
	v_cvt_pk_bf16_f32 v225, v60, v61
	v_cvt_pk_bf16_f32 v230, v62, v63
	v_cvt_pk_bf16_f32 v231, v64, v65
	v_mfma_f32_32x32x16_bf16 v[30:45], v[138:141], v[152:155], v[30:45]
	ds_read_b128 v[138:141], v162 offset:6656
	global_load_dwordx4 v[126:129], v226, s[54:55]
	v_cvt_pk_bf16_f32 v232, v66, v67
	v_cvt_pk_bf16_f32 v233, v68, v69
	v_add_f32_e32 v238, v238, v66
	v_add_f32_e32 v239, v239, v67
	v_add_f32_e32 v242, v242, v68
	v_add_f32_e32 v243, v243, v69
	v_mfma_f32_32x32x16_bf16 v[14:29], v[142:145], v[222:225], v[14:29]
	ds_read_b128 v[142:145], v162 offset:32
	v_cvt_pk_bf16_f32 v234, v70, v71
	v_cvt_pk_bf16_f32 v235, v72, v73
	v_cvt_pk_bf16_f32 v236, v74, v75
	v_cvt_pk_bf16_f32 v237, v76, v77
	v_add_f32_e32 v238, v238, v70
	v_add_f32_e32 v239, v239, v71
	v_mfma_f32_32x32x16_bf16 v[30:45], v[168:171], v[222:225], v[30:45]
	ds_read_b128 v[168:171], v162 offset:6688
	s_and_saveexec_b64 s[4:5], s[6:7]
	s_cbranch_execz .Lmla_nokr0
	global_load_dwordx4 v[122:125], v228, s[56:57]
.Lmla_nokr0:
	s_or_b64 exec, exec, s[4:5]
	v_add_f32_e32 v242, v242, v72
	v_add_f32_e32 v243, v243, v73
	v_add_f32_e32 v238, v238, v74
	v_add_f32_e32 v239, v239, v75
	v_add_f32_e32 v242, v242, v76
	v_add_f32_e32 v243, v243, v77
	v_add_f32_e32 v238, v238, v239
	v_mfma_f32_32x32x16_bf16 v[14:29], v[172:175], v[230:233], v[14:29]
	ds_read_b128 v[172:175], v162 offset:64
	v_add_f32_e32 v242, v242, v243
	v_add_f32_e32 v238, v238, v242
	v_add_f32_e32 v165, v165, v238
	v_max3_f32 v240, v78, v79, v80
	v_max3_f32 v241, v81, v82, v83
	v_max3_f32 v240, v240, v84, v85
	v_mfma_f32_32x32x16_bf16 v[30:45], v[178:181], v[230:233], v[30:45]
	ds_read_b128 v[178:181], v162 offset:6720
	global_load_dwordx4 v[130:133], v227, s[54:55]
	s_add_u32 s54, s54, 0x10000
	s_addc_u32 s55, s55, 0
	s_add_u32 s56, s56, 0x1000
	s_addc_u32 s57, s57, 0
	v_max3_f32 v241, v241, v86, v87
	v_max3_f32 v240, v240, v88, v89
	v_max3_f32 v241, v241, v90, v91
	v_max3_f32 v240, v240, v92, v93
	v_max3_f32 v241, v241, v94, v95
	v_max3_f32 v240, v240, v96, v97
	v_mfma_f32_32x32x16_bf16 v[14:29], v[182:185], v[234:237], v[14:29]
	ds_read_b128 v[182:185], v162 offset:96
	v_max3_f32 v241, v241, v98, v99
	v_max3_f32 v240, v240, v100, v101
	v_max3_f32 v241, v241, v102, v103
	v_max3_f32 v240, v240, v104, v105
	v_max3_f32 v241, v241, v106, v107
	v_mfma_f32_32x32x16_bf16 v[30:45], v[186:189], v[234:237], v[30:45]
	ds_read_b128 v[186:189], v162 offset:6752
	v_max3_f32 v240, v240, v108, v109
	v_max_f32_e32 v240, v240, v241
	v_mov_b32_e32 v241, v240
	s_nop 1
	v_permlane32_swap_b32_e32 v240, v241
	v_max_f32_e32 v244, v240, v241
	v_cmp_lt_f32_e32 vcc, 0x41800000, v244
	s_cbranch_vccnz .Lmla_resc1
.Lmla_resc_ret1:
	s_waitcnt lgkmcnt(7)
	v_mfma_f32_32x32x16_bf16 v[46:61], v[134:137], v[0:3], v[190:205]
	ds_read_b64_tr_b16 v[134:135], v161 offset:34816
	ds_read_b64_tr_b16 v[136:137], v161 offset:35328
	v_exp_f32_e32 v78, v78
	v_exp_f32_e32 v79, v79
	v_exp_f32_e32 v80, v80
	v_exp_f32_e32 v81, v81
	s_waitcnt lgkmcnt(8)
	v_mfma_f32_32x32x16_bf16 v[62:77], v[138:141], v[0:3], v[190:205]
	ds_read_b64_tr_b16 v[138:139], v161 offset:38912
	ds_read_b64_tr_b16 v[140:141], v161 offset:39424
	v_exp_f32_e32 v82, v82
	v_exp_f32_e32 v83, v83
	v_exp_f32_e32 v84, v84
	v_exp_f32_e32 v85, v85
	s_waitcnt lgkmcnt(9)
	v_mfma_f32_32x32x16_bf16 v[46:61], v[142:145], v[4:7], v[46:61]
	ds_read_b64_tr_b16 v[142:143], v161 offset:35840
	ds_read_b64_tr_b16 v[144:145], v161 offset:36352
	v_cvt_pk_bf16_f32 v152, v78, v79
	v_cvt_pk_bf16_f32 v153, v80, v81
	v_cvt_pk_bf16_f32 v154, v82, v83
	v_cvt_pk_bf16_f32 v155, v84, v85
	s_waitcnt lgkmcnt(10)
	v_mfma_f32_32x32x16_bf16 v[62:77], v[168:171], v[4:7], v[62:77]
	ds_read_b64_tr_b16 v[168:169], v161 offset:39936
	ds_read_b64_tr_b16 v[170:171], v161 offset:40448
	v_exp_f32_e32 v86, v86
	v_exp_f32_e32 v87, v87
	v_exp_f32_e32 v88, v88
	v_exp_f32_e32 v89, v89
	s_waitcnt lgkmcnt(11)
	v_mfma_f32_32x32x16_bf16 v[46:61], v[172:175], v[8:11], v[46:61]
	ds_read_b64_tr_b16 v[172:173], v161 offset:36864
	ds_read_b64_tr_b16 v[174:175], v161 offset:37376
	v_exp_f32_e32 v90, v90
	v_exp_f32_e32 v91, v91
	v_exp_f32_e32 v92, v92
	s_waitcnt lgkmcnt(12)
	v_mfma_f32_32x32x16_bf16 v[62:77], v[178:181], v[8:11], v[62:77]
	ds_read_b64_tr_b16 v[178:179], v161 offset:40960
	ds_read_b64_tr_b16 v[180:181], v161 offset:41472
	v_exp_f32_e32 v93, v93
	v_add_f32_e32 v238, v78, v79
	v_add_f32_e32 v239, v80, v81
	v_add_f32_e32 v242, v82, v83
	v_add_f32_e32 v243, v84, v85
	v_exp_f32_e32 v94, v94
	s_waitcnt lgkmcnt(13)
	v_mfma_f32_32x32x16_bf16 v[46:61], v[182:185], v[110:113], v[46:61]
	ds_read_b64_tr_b16 v[182:183], v161 offset:37888
	ds_read_b64_tr_b16 v[184:185], v161 offset:38400
	v_exp_f32_e32 v95, v95
	v_exp_f32_e32 v96, v96
	v_exp_f32_e32 v97, v97
	v_exp_f32_e32 v98, v98
	s_waitcnt lgkmcnt(14)
	v_mfma_f32_32x32x16_bf16 v[62:77], v[186:189], v[110:113], v[62:77]
	s_waitcnt lgkmcnt(13)
	ds_read_b64_tr_b16 v[186:187], v161 offset:41984
	ds_read_b64_tr_b16 v[188:189], v161 offset:42496
	v_exp_f32_e32 v99, v99
	v_exp_f32_e32 v100, v100
	v_exp_f32_e32 v101, v101
	v_mfma_f32_32x32x16_bf16 v[46:61], v[206:209], v[114:117], v[46:61]
	v_add_f32_e32 v238, v238, v86
	v_add_f32_e32 v239, v239, v87
	v_add_f32_e32 v242, v242, v88
	v_add_f32_e32 v243, v243, v89
	v_add_f32_e32 v238, v238, v90
	v_add_f32_e32 v239, v239, v91
	v_add_f32_e32 v242, v242, v92
	s_waitcnt lgkmcnt(8)
	s_waitcnt vmcnt(0)
	ds_write_b128 v158, v[126:129] offset:13312
	s_and_saveexec_b64 s[4:5], s[6:7]
	s_cbranch_execz .Lmla_nokw1
	ds_write_b128 v163, v[122:125] offset:13440
.Lmla_nokw1:
	s_or_b64 exec, exec, s[4:5]
	ds_write_b128 v159, v[130:133] offset:26624
	v_mfma_f32_32x32x16_bf16 v[62:77], v[210:213], v[114:117], v[62:77]
	v_add_f32_e32 v243, v243, v93
	v_exp_f32_e32 v102, v102
	v_exp_f32_e32 v103, v103
	v_exp_f32_e32 v104, v104
	v_mfma_f32_32x32x16_bf16 v[46:61], v[214:217], v[118:121], v[46:61]
	v_exp_f32_e32 v105, v105
	v_exp_f32_e32 v106, v106
	v_exp_f32_e32 v107, v107
	v_exp_f32_e32 v108, v108
	v_mfma_f32_32x32x16_bf16 v[62:77], v[248:251], v[118:121], v[62:77]
	v_exp_f32_e32 v109, v109
	v_add_f32_e32 v238, v238, v94
	v_add_f32_e32 v239, v239, v95
	v_add_f32_e32 v242, v242, v96
	v_add_f32_e32 v243, v243, v97
	s_waitcnt lgkmcnt(0)
	s_barrier
	ds_read_b128 v[206:209], v162 offset:13440
	ds_read_b128 v[210:213], v162 offset:20096
	ds_read_b128 v[214:217], v162 offset:13472
	ds_read_b128 v[248:251], v162 offset:20128
	v_mfma_f32_32x32x16_bf16 v[14:29], v[134:137], v[152:155], v[14:29]
	ds_read_b128 v[134:137], v162 offset:13312
	v_cvt_pk_bf16_f32 v222, v86, v87
	v_cvt_pk_bf16_f32 v223, v88, v89
	v_cvt_pk_bf16_f32 v224, v90, v91
	v_cvt_pk_bf16_f32 v225, v92, v93
	v_cvt_pk_bf16_f32 v230, v94, v95
	v_cvt_pk_bf16_f32 v231, v96, v97
	v_mfma_f32_32x32x16_bf16 v[30:45], v[138:141], v[152:155], v[30:45]
	ds_read_b128 v[138:141], v162 offset:19968
	global_load_dwordx4 v[126:129], v226, s[54:55]
	v_cvt_pk_bf16_f32 v232, v98, v99
	v_cvt_pk_bf16_f32 v233, v100, v101
	v_add_f32_e32 v238, v238, v98
	v_add_f32_e32 v239, v239, v99
	v_add_f32_e32 v242, v242, v100
	v_add_f32_e32 v243, v243, v101
	v_mfma_f32_32x32x16_bf16 v[14:29], v[142:145], v[222:225], v[14:29]
	ds_read_b128 v[142:145], v162 offset:13344
	v_cvt_pk_bf16_f32 v234, v102, v103
	v_cvt_pk_bf16_f32 v235, v104, v105
	v_cvt_pk_bf16_f32 v236, v106, v107
	v_cvt_pk_bf16_f32 v237, v108, v109
	v_add_f32_e32 v238, v238, v102
	v_add_f32_e32 v239, v239, v103
	v_mfma_f32_32x32x16_bf16 v[30:45], v[168:171], v[222:225], v[30:45]
	ds_read_b128 v[168:171], v162 offset:20000
	s_and_saveexec_b64 s[4:5], s[6:7]
	s_cbranch_execz .Lmla_nokr1
	global_load_dwordx4 v[122:125], v228, s[56:57]
.Lmla_nokr1:
	s_or_b64 exec, exec, s[4:5]
	v_add_f32_e32 v242, v242, v104
	v_add_f32_e32 v243, v243, v105
	v_add_f32_e32 v238, v238, v106
	v_add_f32_e32 v239, v239, v107
	v_add_f32_e32 v242, v242, v108
	v_add_f32_e32 v243, v243, v109
	v_add_f32_e32 v238, v238, v239
	v_mfma_f32_32x32x16_bf16 v[14:29], v[172:175], v[230:233], v[14:29]
	ds_read_b128 v[172:175], v162 offset:13376
	v_add_f32_e32 v242, v242, v243
	v_add_f32_e32 v238, v238, v242
	v_add_f32_e32 v165, v165, v238
	v_max3_f32 v240, v46, v47, v48
	v_max3_f32 v241, v49, v50, v51
	v_max3_f32 v240, v240, v52, v53
	v_mfma_f32_32x32x16_bf16 v[30:45], v[178:181], v[230:233], v[30:45]
	ds_read_b128 v[178:181], v162 offset:20032
	global_load_dwordx4 v[130:133], v227, s[54:55]
	s_add_u32 s54, s54, 0x10000
	s_addc_u32 s55, s55, 0
	s_add_u32 s56, s56, 0x1000
	s_addc_u32 s57, s57, 0
	v_max3_f32 v241, v241, v54, v55
	v_max3_f32 v240, v240, v56, v57
	v_max3_f32 v241, v241, v58, v59
	v_max3_f32 v240, v240, v60, v61
	v_max3_f32 v241, v241, v62, v63
	v_max3_f32 v240, v240, v64, v65
	v_mfma_f32_32x32x16_bf16 v[14:29], v[182:185], v[234:237], v[14:29]
	ds_read_b128 v[182:185], v162 offset:13408
	v_max3_f32 v241, v241, v66, v67
	v_max3_f32 v240, v240, v68, v69
	v_max3_f32 v241, v241, v70, v71
	v_max3_f32 v240, v240, v72, v73
	v_max3_f32 v241, v241, v74, v75
	v_mfma_f32_32x32x16_bf16 v[30:45], v[186:189], v[234:237], v[30:45]
	ds_read_b128 v[186:189], v162 offset:20064
	v_max3_f32 v240, v240, v76, v77
	v_max_f32_e32 v240, v240, v241
	v_mov_b32_e32 v241, v240
	s_nop 1
	v_permlane32_swap_b32_e32 v240, v241
	v_max_f32_e32 v244, v240, v241
	s_add_i32 s10, s10, 2
	s_add_i32 s4, s35, 2
	s_cmp_ge_u32 s10, s4
	s_cbranch_scc0 .Lmla_loop
	s_waitcnt vmcnt(0) lgkmcnt(0)
	v_add_f32_e32 v46, v46, v164
	v_add_f32_e32 v47, v47, v164
	v_add_f32_e32 v48, v48, v164
	v_add_f32_e32 v49, v49, v164
	v_add_f32_e32 v50, v50, v164
	v_add_f32_e32 v51, v51, v164
	v_add_f32_e32 v52, v52, v164
	v_add_f32_e32 v53, v53, v164
	v_add_f32_e32 v54, v54, v164
	v_add_f32_e32 v55, v55, v164
	v_add_f32_e32 v56, v56, v164
	v_add_f32_e32 v57, v57, v164
	v_add_f32_e32 v58, v58, v164
	v_add_f32_e32 v59, v59, v164
	v_add_f32_e32 v60, v60, v164
	v_add_f32_e32 v61, v61, v164
	v_add_f32_e32 v62, v62, v164
	v_add_f32_e32 v63, v63, v164
	v_add_f32_e32 v64, v64, v164
	v_add_f32_e32 v65, v65, v164
	v_add_f32_e32 v66, v66, v164
	v_add_f32_e32 v67, v67, v164
	v_add_f32_e32 v68, v68, v164
	v_add_f32_e32 v69, v69, v164
	v_add_f32_e32 v70, v70, v164
	v_add_f32_e32 v71, v71, v164
	v_add_f32_e32 v72, v72, v164
	v_add_f32_e32 v73, v73, v164
	v_add_f32_e32 v74, v74, v164
	v_add_f32_e32 v75, v75, v164
	v_add_f32_e32 v76, v76, v164
	v_add_f32_e32 v77, v77, v164
	s_barrier
	s_branch .LBB0_738
